# mixer B: QK MFMA chain placed inside the raised-priority window (s_setprio 0 moved behind the chain)
# baseline (speedup 1.0000x reference)
; DI size_t zrowU(int row0, int NT) { return ((size_t)((row0 >> 8) * NT) << 16) + (size_t)((((row0 >> 7) & 1) << 15) | (((row0 >> 5) & 1) << 14) | (((row0 >> 6) & 1) << 11)); }
; #define MFMA32(a, b, c) __builtin_amdgcn_mfma_f32_32x32x16_bf16((a), (b), (c), 0, 0, 0)
; DI void attnB_item(bf16_t* z, int hh, int qs, LAS bf16_t* vs, int lane) {
;     ...
;         const int kpos0 = t < 0 ? 0 : NMETA + 32 * t, kvalid = t < 0 ? NMETA : 32;
;         const int tn = t <= 0 ? -1 : t - 1;
;         const size_t ron = zrowU(tn < 0 ? SEQ : 32 * tn, 32);
;         f32x16 S; bf16x8 qf[8];
; #pragma unroll
;         for (int i = 0; i < 16; ++i) S[i] = 0.f;
; #pragma unroll
;         for (int s = 0; s < 8; ++s) qf[s] = qs_lds[64 * s];
;         asm volatile("s_waitcnt lgkmcnt(0)" ::: "memory"); __builtin_amdgcn_sched_barrier(0);
;         __builtin_amdgcn_s_setprio(1);
; #pragma unroll
;         for (int s = 0; s < 8; ++s) S = MFMA32(kf[s], qf[s], S);
;         __builtin_amdgcn_s_setprio(0);
; #pragma unroll
;         for (int s = 0; s < 8; ++s) kf[s] = *(const bf16x8*)(kbase + ron + (((s >> 1) << 9) | ((s & 1) << 8)));
.LBB0_151:
	s_waitcnt vmcnt(8)
	v_mov_b64_e32 v[148:149], v[144:145]
	v_mov_b64_e32 v[146:147], v[142:143]
	s_cmp_lt_i32 s30, 0
	ds_read_b128 v[66:69], v182 offset:10240
	ds_read_b128 v[142:145], v182 offset:11264
	ds_read_b128 v[150:153], v182 offset:12288
	ds_read_b128 v[192:195], v182 offset:13312
	ds_read_b128 v[196:199], v182 offset:14336
	ds_read_b128 v[200:203], v182 offset:15360
	ds_read_b128 v[204:207], v182 offset:16384
	ds_read_b128 v[208:211], v182 offset:17408
	s_cselect_b64 s[8:9], -1, 0
	s_cmp_gt_i32 s30, -1
	s_cselect_b64 s[4:5], -1, 0
	s_max_i32 s29, s30, 0
	s_add_i32 s29, s29, -1
	s_lshl_b32 s6, s29, 5
	s_cmp_gt_i32 s30, 0
	s_cselect_b32 s10, s6, 0x4000
	s_ashr_i32 s6, s10, 3
	s_lshl_b32 s11, s10, 8
	s_lshl_b32 s31, s10, 9
	s_andn2_b32 s6, s6, 31
	s_and_b32 s11, s11, 0x8000
	s_and_b32 s31, s31, 0x4000
	s_lshl_b32 s10, s10, 5
	s_waitcnt lgkmcnt(0)
	s_ashr_i32 s7, s6, 31
	s_or_b32 s11, s11, s31
	s_and_b32 s10, s10, 0x800
	s_or_b32 s10, s11, s10
	s_lshl_b64 s[6:7], s[6:7], 16
	s_setprio 1
	s_or_b32 s6, s6, s10
	s_waitcnt lgkmcnt(7)
	v_mfma_f32_32x32x16_bf16 v[66:81], v[114:117], v[66:69], 0
	s_cmp_lg_u32 s30, s28
	s_cselect_b64 s[10:11], -1, 0
	s_and_b64 s[38:39], s[10:11], s[4:5]
	s_mov_b64 s[10:11], -1
	v_add_f32_e32 v191, 0, v189
	s_and_b64 vcc, exec, s[38:39]
	s_waitcnt lgkmcnt(6)
	v_mfma_f32_32x32x16_bf16 v[66:81], v[118:121], v[142:145], v[66:81]
	v_lshl_add_u64 v[142:143], s[6:7], 1, v[158:159]
	s_waitcnt lgkmcnt(5)
	v_mfma_f32_32x32x16_bf16 v[66:81], v[122:125], v[150:153], v[66:81]
	s_waitcnt lgkmcnt(4)
	v_mfma_f32_32x32x16_bf16 v[66:81], v[126:129], v[192:195], v[66:81]
	s_waitcnt lgkmcnt(3)
	v_mfma_f32_32x32x16_bf16 v[66:81], v[130:133], v[196:199], v[66:81]
	s_waitcnt lgkmcnt(2)
	v_mfma_f32_32x32x16_bf16 v[66:81], v[134:137], v[200:203], v[66:81]
	global_load_dwordx4 v[114:117], v[142:143], off
	global_load_dwordx4 v[118:121], v[142:143], off offset:512
	global_load_dwordx4 v[122:125], v[142:143], off offset:1024
	global_load_dwordx4 v[126:129], v[142:143], off offset:1536
	global_load_dwordx4 v[130:133], v[142:143], off offset:2048
	global_load_dwordx4 v[134:137], v[142:143], off offset:2560
	s_waitcnt lgkmcnt(1)
	v_mfma_f32_32x32x16_bf16 v[66:81], v[138:141], v[204:207], v[66:81]
	global_load_dwordx4 v[138:141], v[142:143], off offset:3072
	s_nop 0
	global_load_dwordx4 v[142:145], v[142:143], off offset:3584
	s_waitcnt lgkmcnt(0)
	v_mfma_f32_32x32x16_bf16 v[66:81], v[146:149], v[208:211], v[66:81]
	s_setprio 0
	s_nop 11
	v_mul_f32_e32 v207, 0x3e0293ee, v66
	v_mul_f32_e32 v206, 0x3e0293ee, v67
	v_mul_f32_e32 v205, 0x3e0293ee, v68
	v_mul_f32_e32 v204, 0x3e0293ee, v69
	v_mul_f32_e32 v203, 0x3e0293ee, v70
	v_mul_f32_e32 v202, 0x3e0293ee, v71
	v_mul_f32_e32 v201, 0x3e0293ee, v72
	v_mul_f32_e32 v200, 0x3e0293ee, v73
	v_mul_f32_e32 v199, 0x3e0293ee, v74
	v_mul_f32_e32 v198, 0x3e0293ee, v75
	v_mul_f32_e32 v197, 0x3e0293ee, v76
	v_mul_f32_e32 v196, 0x3e0293ee, v77
	v_mul_f32_e32 v195, 0x3e0293ee, v78
	v_mul_f32_e32 v194, 0x3e0293ee, v79
	v_mul_f32_e32 v193, 0x3e0293ee, v80
	v_mul_f32_e32 v192, 0x3e0293ee, v81
	s_cbranch_vccz .LBB0_153
; DI unsigned pk2(float a, float b) { f32x2 v = {a, b}; bf16v2 r = __builtin_convertvector(v, bf16v2); return __builtin_bit_cast(unsigned, r); }
; DI float shflx(float v, int mask, int lane) { return __int_as_float(__builtin_amdgcn_ds_bpermute((lane ^ mask) << 2, __float_as_int(v))); }
; template <bool MASKED>
; DI void attnB_tile_math(const f32x16& S, int kpos0, int kvalid, int qpos, int h, int lane, float& later, unsigned (&pw)[8]) {
;     const float scale2 = 0.08838834764831845f * 1.4426950408889634f;
;     float x2[16], sp[16];
; #pragma unroll
;     for (int r = 0; r < 16; ++r) {
;         const float x = S[r] * scale2; x2[r] = x;
;         const float e = __builtin_amdgcn_exp2f(-fabsf(x));
;         const float v = fmaxf(x, 0.f) + __builtin_amdgcn_logf(1.0f + e);
;         if (MASKED) { const int row = (r & 3) + 8 * (r >> 2) + 4 * h; const bool vis = (row < kvalid) && (kpos0 + row < qpos); sp[r] = vis ? v : 0.f; }
;         else sp[r] = v;
;     }
;     float G[4], P[4];
; #pragma unroll
;     for (int g = 0; g < 4; ++g) { G[g] = (sp[4 * g] + sp[4 * g + 1]) + (sp[4 * g + 2] + sp[4 * g + 3]); P[g] = shflx(G[g], 32, lane); }
;     float R[4]; R[3] = 0.f; R[2] = G[3] + P[3]; R[1] = R[2] + (G[2] + P[2]); R[0] = R[1] + (G[1] + P[1]);
;     const float total = R[0] + (G[0] + P[0]);
; #pragma unroll
;     for (int g = 0; g < 4; ++g) {
;         float sfx = later + R[g] + (h == 0 ? P[g] : 0.f); float wv[4];
; #pragma unroll
;         for (int i = 3; i >= 0; --i) {
;             const int r = 4 * g + i;
;             sfx += sp[r];
;             float t = __builtin_amdgcn_exp2f(x2[r] - sfx);
;             if (MASKED) { const int row = (r & 3) + 8 * (r >> 2) + 4 * h; const bool vis = (row < kvalid) && (kpos0 + row < qpos); t = vis ? t : 0.f; }
;             wv[i] = t;
;         }
;         pw[2 * g] = pk2(wv[0], wv[1]); pw[2 * g + 1] = pk2(wv[2], wv[3]);
;     }
;     later += total;
; }
	v_exp_f32_e64 v147, -|v206|
	v_max_f32_e32 v149, 0, v206
	v_exp_f32_e64 v151, -|v205|
	v_max_f32_e32 v214, 0, v203
	v_add_f32_e32 v147, 1.0, v147
	v_log_f32_e32 v147, v147
	v_max_f32_e32 v215, 0, v202
	v_exp_f32_e64 v148, -|v207|
	v_max_f32_e32 v218, 0, v201
	v_add_f32_e32 v150, v149, v147
	v_exp_f32_e64 v147, -|v204|
	v_add_f32_e32 v149, 1.0, v151
	v_log_f32_e32 v208, v149
	v_exp_f32_e64 v149, -|v203|
	v_add_f32_e32 v147, 1.0, v147
	v_log_f32_e32 v212, v147
	v_exp_f32_e64 v147, -|v202|
	v_add_f32_e32 v149, 1.0, v149
	v_log_f32_e32 v216, v149
	v_exp_f32_e64 v149, -|v200|
	v_add_f32_e32 v147, 1.0, v147
	v_log_f32_e32 v217, v147
	v_exp_f32_e64 v147, -|v201|
	v_add_f32_e32 v148, 1.0, v148
	v_max_f32_e32 v219, 0, v200
	v_pk_add_f32 v[214:215], v[214:215], v[216:217]
	v_add_f32_e32 v147, 1.0, v147
	v_log_f32_e32 v216, v147
	v_add_f32_e32 v147, 1.0, v149
	v_log_f32_e32 v217, v147
	v_exp_f32_e64 v147, -|v199|
	v_exp_f32_e64 v149, -|v198|
	v_log_f32_e32 v148, v148
	v_pk_add_f32 v[216:217], v[218:219], v[216:217]
	v_add_f32_e32 v147, 1.0, v147
	v_log_f32_e32 v220, v147
	v_add_f32_e32 v147, 1.0, v149
	v_exp_f32_e64 v149, -|v197|
	v_log_f32_e32 v224, v147
	v_exp_f32_e64 v147, -|v196|
	v_max_f32_e32 v218, 0, v199
	v_add_f32_e32 v149, 1.0, v149
	v_log_f32_e32 v221, v149
	v_add_f32_e32 v147, 1.0, v147
	v_exp_f32_e64 v149, -|v195|
	v_log_f32_e32 v225, v147
	v_exp_f32_e64 v147, -|v194|
	v_max_f32_e32 v222, 0, v198
	v_add_f32_e32 v149, 1.0, v149
	v_log_f32_e32 v228, v149
	v_add_f32_e32 v147, 1.0, v147
	v_exp_f32_e64 v149, -|v193|
	v_log_f32_e32 v232, v147
	v_exp_f32_e64 v147, -|v192|
	v_max_f32_e32 v219, 0, v197
	v_add_f32_e32 v149, 1.0, v149
	v_log_f32_e32 v229, v149
	v_add_f32_e32 v147, 1.0, v147
	v_log_f32_e32 v233, v147
	v_max_f32_e32 v223, 0, v196
	v_max_f32_e32 v226, 0, v195
	v_max_f32_e32 v230, 0, v194
	v_max_f32_e32 v227, 0, v193
	v_max_f32_e32 v231, 0, v192
	v_pk_add_f32 v[218:219], v[218:219], v[220:221]
	v_pk_add_f32 v[220:221], v[222:223], v[224:225]
	v_pk_add_f32 v[224:225], v[226:227], v[228:229]
	v_pk_add_f32 v[226:227], v[230:231], v[232:233]
	v_pk_add_f32 v[234:235], v[214:215], v[214:215] op_sel_hi:[0,1]
	v_pk_add_f32 v[236:237], v[216:217], v[216:217] op_sel_hi:[0,1]
	v_pk_add_f32 v[222:223], v[218:219], v[220:221]
	v_pk_add_f32 v[228:229], v[224:225], v[226:227]
	v_max_f32_e32 v146, 0, v207
	v_pk_add_f32 v[222:223], v[222:223], v[222:223] op_sel:[0,1] op_sel_hi:[1,0]
	v_pk_add_f32 v[228:229], v[228:229], v[228:229] op_sel:[0,1] op_sel_hi:[1,0]
	v_mov_b32_e32 v147, v235
	v_mov_b32_e32 v149, v237
	ds_bpermute_b32 v209, v184, v222
	ds_bpermute_b32 v213, v184, v228
	v_pk_add_f32 v[146:147], v[146:147], v[148:149]
	ds_bpermute_b32 v151, v184, v147
	v_max_f32_e32 v152, 0, v205
	v_max_f32_e32 v210, 0, v204
	v_mov_b32_e32 v211, v228
	v_mov_b32_e32 v153, v222
	s_waitcnt lgkmcnt(1)
	v_pk_add_f32 v[210:211], v[210:211], v[212:213]
	v_pk_add_f32 v[148:149], v[152:153], v[208:209]
	s_waitcnt lgkmcnt(0)
	v_pk_add_f32 v[222:223], v[146:147], v[150:151]
	v_pk_add_f32 v[152:153], v[148:149], v[210:211]
	v_cndmask_b32_e64 v151, 0, v151, s[36:37]
	v_pk_add_f32 v[222:223], v[222:223], v[152:153]
	ds_bpermute_b32 v208, v184, v222
	v_add_f32_e32 v147, v189, v223
	s_mov_b64 s[10:11], 0
	s_waitcnt lgkmcnt(0)
	v_cndmask_b32_e64 v149, 0, v208, s[36:37]
	v_add_f32_e32 v147, v149, v147
	v_add_f32_e32 v147, v210, v147
	v_fma_f32 v149, v69, s16, -v147
	v_add_f32_e32 v147, v148, v147
	v_fma_f32 v148, v68, s16, -v147
	v_add_f32_e32 v147, v150, v147
	v_fma_f32 v150, v67, s16, -v147
	v_add_f32_e32 v146, v146, v147
	v_add_f32_e32 v147, v189, v153
	v_add_f32_e32 v147, v151, v147
	v_add_f32_e32 v147, v217, v147
	v_fma_f32 v151, v73, s16, -v147
	v_add_f32_e32 v147, v216, v147
	v_fma_f32 v146, v66, s16, -v146
	v_fma_f32 v152, v72, s16, -v147
	v_exp_f32_e32 v149, v149
	v_exp_f32_e32 v148, v148
	v_exp_f32_e32 v150, v150
	v_exp_f32_e32 v146, v146
	v_exp_f32_e32 v151, v151
	v_add_f32_e32 v147, v215, v147
	v_exp_f32_e32 v152, v152
	v_fma_f32 v153, v71, s16, -v147
	v_add_f32_e32 v147, v214, v147
	v_fma_f32 v147, v70, s16, -v147
	v_exp_f32_e32 v153, v153
	v_exp_f32_e32 v210, v147
	v_cvt_pk_bf16_f32 v146, v146, v150
	v_cvt_pk_bf16_f32 v147, v148, v149
	v_cvt_pk_bf16_f32 v149, v152, v151
	v_add_f32_e32 v150, v189, v211
	v_cndmask_b32_e64 v151, 0, v209, s[36:37]
	v_cndmask_b32_e64 v209, 0, v213, s[36:37]
	v_add_f32_e32 v150, v151, v150
	v_add_f32_e32 v209, v191, v209
	v_add_f32_e32 v150, v221, v150
	v_add_f32_e32 v209, v227, v209
	v_cvt_pk_bf16_f32 v148, v210, v153
	v_fma_f32 v151, v77, s16, -v150
	v_add_f32_e32 v150, v219, v150
	v_fma_f32 v210, v81, s16, -v209
	v_add_f32_e32 v209, v225, v209
	v_fma_f32 v152, v76, s16, -v150
	v_add_f32_e32 v150, v220, v150
	v_fma_f32 v211, v80, s16, -v209
	v_add_f32_e32 v209, v226, v209
	v_fma_f32 v153, v75, s16, -v150
	v_add_f32_e32 v150, v218, v150
	v_fma_f32 v212, v79, s16, -v209
	v_add_f32_e32 v209, v224, v209
	v_fma_f32 v150, v74, s16, -v150
	v_fma_f32 v209, v78, s16, -v209
	v_exp_f32_e32 v151, v151
	v_exp_f32_e32 v152, v152
	v_exp_f32_e32 v153, v153
	v_exp_f32_e32 v150, v150
	v_exp_f32_e32 v210, v210
	v_exp_f32_e32 v212, v212
	v_exp_f32_e32 v209, v209
	v_exp_f32_e32 v211, v211
	v_add_f32_e32 v208, v222, v208
	v_cvt_pk_bf16_f32 v150, v150, v153
	v_cvt_pk_bf16_f32 v151, v152, v151
	v_cvt_pk_bf16_f32 v152, v209, v212
	v_cvt_pk_bf16_f32 v153, v211, v210
	v_add_f32_e32 v208, v208, v223
